# diff-attention unit epilogue: sub-layer-norm gain loads issued once up front instead of 8 serialized load/full-wait/store groups
# speedup vs baseline: 1.0139x; 1.0024x over previous
; __device__ __forceinline__ float frcp(float x) { return __builtin_amdgcn_rcpf(x); }
; __device__ __forceinline__ float xsum16(float x) { auto r = __builtin_amdgcn_permlane16_swap(__float_as_uint(x), __float_as_uint(x), false, false); return __uint_as_float(r[0]) + __uint_as_float(r[1]); }
; __device__ __forceinline__ float xsum32(float x) { auto r = __builtin_amdgcn_permlane32_swap(__float_as_uint(x), __float_as_uint(x), false, false); return __uint_as_float(r[0]) + __uint_as_float(r[1]); }
; __device__ __forceinline__ void diff_unit(LAS unsigned char* lds, const bf16_t* zA, bf16_t* ya, int bl, int h, int qt, float slope, float lam, float oml, const float* subln, int tid) {
;     ...
;     la = xsum32(xsum16(la)); lb = xsum32(xsum16(lb));
;     const float ila = frcp(la), ilb = lam * frcp(lb);
;     float ss = 0.f;
; #pragma unroll
;     for (int d = 0; d < 8; ++d) { oa[d] = oa[d] * ila - ob[d] * ilb; ss += (oa[d][0] * oa[d][0] + oa[d][1] * oa[d][1]) + (oa[d][2] * oa[d][2] + oa[d][3] * oa[d][3]); }
;     ss = xsum32(xsum16(ss));
;     const float rn = oml / sqrtf(ss * (1.f / 128.f) + 1e-6f);
;     bf16_t* yp = ya + (rb + qpos) * 1536 + h * 128 + quad * 4;
.LBB0_222:
	s_nop 0
	v_mov_b32_e32 v0, v134
	s_nop 1
	v_permlane16_swap_b32_e32 v134, v0
	v_add_f32_e32 v0, v134, v0
	v_mov_b32_e32 v1, v0
	s_nop 1
	v_permlane32_swap_b32_e32 v0, v1
	v_add_f32_e32 v0, v0, v1
	v_mov_b32_e32 v1, v135
	s_nop 1
	v_permlane16_swap_b32_e32 v135, v1
	v_add_f32_e32 v1, v135, v1
	v_mov_b32_e32 v3, v1
	s_nop 1
	v_permlane32_swap_b32_e32 v1, v3
	v_add_f32_e32 v1, v1, v3
	v_rcp_f32_e32 v1, v1
	v_rcp_f32_e32 v0, v0
	v_readlane_b32 s12, v255, 46
	v_readlane_b32 s13, v255, 47
	v_mul_f32_e32 v4, v150, v1
	v_pk_mul_f32 v[6:7], v[70:71], v[4:5] op_sel_hi:[1,0]
	v_pk_mul_f32 v[8:9], v[68:69], v[4:5] op_sel_hi:[1,0]
	v_pk_fma_f32 v[68:69], v[38:39], v[0:1], v[6:7] op_sel_hi:[1,0,1] neg_lo:[0,0,1] neg_hi:[0,0,1]
	v_pk_fma_f32 v[70:71], v[36:37], v[0:1], v[8:9] op_sel_hi:[1,0,1] neg_lo:[0,0,1] neg_hi:[0,0,1]
	v_mul_f32_e32 v3, v69, v69
	v_mul_f32_e32 v1, v71, v71
	v_fmac_f32_e32 v1, v70, v70
	v_fmac_f32_e32 v3, v68, v68
	v_add_f32_e32 v1, v1, v3
	v_pk_mul_f32 v[6:7], v[66:67], v[4:5] op_sel_hi:[1,0]
	v_pk_mul_f32 v[8:9], v[64:65], v[4:5] op_sel_hi:[1,0]
	v_pk_fma_f32 v[64:65], v[34:35], v[0:1], v[6:7] op_sel_hi:[1,0,1] neg_lo:[0,0,1] neg_hi:[0,0,1]
	v_pk_fma_f32 v[66:67], v[32:33], v[0:1], v[8:9] op_sel_hi:[1,0,1] neg_lo:[0,0,1] neg_hi:[0,0,1]
	v_mul_f32_e32 v5, v65, v65
	v_mul_f32_e32 v3, v67, v67
	v_fmac_f32_e32 v3, v66, v66
	v_fmac_f32_e32 v5, v64, v64
	v_add_f32_e32 v3, v3, v5
	v_add_f32_e32 v1, v1, v3
	v_pk_mul_f32 v[6:7], v[50:51], v[4:5] op_sel_hi:[1,0]
	v_pk_mul_f32 v[8:9], v[48:49], v[4:5] op_sel_hi:[1,0]
	v_pk_fma_f32 v[36:37], v[22:23], v[0:1], v[6:7] op_sel_hi:[1,0,1] neg_lo:[0,0,1] neg_hi:[0,0,1]
	v_pk_fma_f32 v[38:39], v[20:21], v[0:1], v[8:9] op_sel_hi:[1,0,1] neg_lo:[0,0,1] neg_hi:[0,0,1]
	v_mul_f32_e32 v5, v37, v37
	v_mul_f32_e32 v3, v39, v39
	v_fmac_f32_e32 v3, v38, v38
	v_fmac_f32_e32 v5, v36, v36
	v_add_f32_e32 v3, v3, v5
	v_add_f32_e32 v1, v3, v1
	v_pk_mul_f32 v[6:7], v[62:63], v[4:5] op_sel_hi:[1,0]
	v_pk_mul_f32 v[8:9], v[60:61], v[4:5] op_sel_hi:[1,0]
	v_pk_fma_f32 v[32:33], v[42:43], v[0:1], v[6:7] op_sel_hi:[1,0,1] neg_lo:[0,0,1] neg_hi:[0,0,1]
	v_pk_fma_f32 v[34:35], v[40:41], v[0:1], v[8:9] op_sel_hi:[1,0,1] neg_lo:[0,0,1] neg_hi:[0,0,1]
	v_mul_f32_e32 v5, v33, v33
	v_mul_f32_e32 v3, v35, v35
	v_fmac_f32_e32 v3, v34, v34
	v_fmac_f32_e32 v5, v32, v32
	v_add_f32_e32 v3, v3, v5
	v_add_f32_e32 v1, v3, v1
	v_pk_mul_f32 v[6:7], v[54:55], v[4:5] op_sel_hi:[1,0]
	v_pk_mul_f32 v[8:9], v[52:53], v[4:5] op_sel_hi:[1,0]
	v_pk_fma_f32 v[22:23], v[30:31], v[0:1], v[6:7] op_sel_hi:[1,0,1] neg_lo:[0,0,1] neg_hi:[0,0,1]
	v_pk_fma_f32 v[28:29], v[28:29], v[0:1], v[8:9] op_sel_hi:[1,0,1] neg_lo:[0,0,1] neg_hi:[0,0,1]
	v_mul_f32_e32 v5, v23, v23
	v_mul_f32_e32 v3, v29, v29
	v_fmac_f32_e32 v3, v28, v28
	v_fmac_f32_e32 v5, v22, v22
	v_add_f32_e32 v3, v3, v5
	v_add_f32_e32 v1, v3, v1
	v_pk_mul_f32 v[6:7], v[58:59], v[4:5] op_sel_hi:[1,0]
	v_pk_mul_f32 v[8:9], v[56:57], v[4:5] op_sel_hi:[1,0]
	v_pk_fma_f32 v[16:17], v[26:27], v[0:1], v[6:7] op_sel_hi:[1,0,1] neg_lo:[0,0,1] neg_hi:[0,0,1]
	v_pk_fma_f32 v[20:21], v[24:25], v[0:1], v[8:9] op_sel_hi:[1,0,1] neg_lo:[0,0,1] neg_hi:[0,0,1]
	v_mul_f32_e32 v5, v17, v17
	v_mul_f32_e32 v3, v21, v21
	v_fmac_f32_e32 v3, v20, v20
	v_fmac_f32_e32 v5, v16, v16
	v_add_f32_e32 v3, v3, v5
	v_add_f32_e32 v1, v3, v1
	v_pk_mul_f32 v[6:7], v[82:83], v[4:5] op_sel_hi:[1,0]
	v_pk_mul_f32 v[8:9], v[80:81], v[4:5] op_sel_hi:[1,0]
	v_pk_fma_f32 v[10:11], v[46:47], v[0:1], v[6:7] op_sel_hi:[1,0,1] neg_lo:[0,0,1] neg_hi:[0,0,1]
	v_pk_fma_f32 v[12:13], v[44:45], v[0:1], v[8:9] op_sel_hi:[1,0,1] neg_lo:[0,0,1] neg_hi:[0,0,1]
	v_mul_f32_e32 v5, v11, v11
	v_mul_f32_e32 v3, v13, v13
	v_fmac_f32_e32 v3, v12, v12
	v_fmac_f32_e32 v5, v10, v10
	v_add_f32_e32 v3, v3, v5
	v_pk_mul_f32 v[6:7], v[78:79], v[4:5] op_sel_hi:[1,0]
	v_pk_mul_f32 v[4:5], v[76:77], v[4:5] op_sel_hi:[1,0]
	v_add_f32_e32 v3, v3, v1
	v_pk_fma_f32 v[8:9], v[72:73], v[0:1], v[4:5] op_sel_hi:[1,0,1] neg_lo:[0,0,1] neg_hi:[0,0,1]
	v_pk_fma_f32 v[0:1], v[74:75], v[0:1], v[6:7] op_sel_hi:[1,0,1] neg_lo:[0,0,1] neg_hi:[0,0,1]
	v_mul_f32_e32 v4, v9, v9
	v_mul_f32_e32 v5, v1, v1
	v_fmac_f32_e32 v4, v8, v8
	v_fmac_f32_e32 v5, v0, v0
	v_add_f32_e32 v4, v4, v5
	v_add_f32_e32 v3, v4, v3
	v_mov_b32_e32 v4, v3
	s_nop 1
	v_permlane16_swap_b32_e32 v3, v4
	v_add_f32_e32 v3, v3, v4
	v_mov_b32_e32 v4, v3
	s_nop 1
	v_permlane32_swap_b32_e32 v3, v4
	v_add_f32_e32 v3, v3, v4
	v_fmamk_f32 v3, v3, 0x3c000000, v175
	v_cmp_gt_f32_e32 vcc, s33, v3
	v_mul_f32_e32 v4, 0x4f800000, v3
	s_add_u32 s44, s44, s12
	v_cndmask_b32_e32 v3, v3, v4, vcc
	v_sqrt_f32_e32 v4, v3
	s_addc_u32 s45, s45, s13
	s_lshl_b32 s30, s14, 1
	v_lshlrev_b32_e32 v188, 2, v139
	global_load_dwordx4 v[192:195], v188, s[44:45]
	global_load_dwordx4 v[196:199], v188, s[44:45] offset:64
	global_load_dwordx4 v[200:203], v188, s[44:45] offset:128
	global_load_dwordx4 v[204:207], v188, s[44:45] offset:192
	global_load_dwordx4 v[208:211], v188, s[44:45] offset:256
	global_load_dwordx4 v[212:215], v188, s[44:45] offset:320
	global_load_dwordx4 v[216:219], v188, s[44:45] offset:384
	global_load_dwordx4 v[220:223], v188, s[44:45] offset:448
	v_add_u32_e32 v5, -1, v4
	v_fma_f32 v6, -v5, v4, v3
	v_cmp_ge_f32_e64 s[42:43], 0, v6
	v_add_u32_e32 v6, 1, v4
	s_barrier
; __device__ __forceinline__ unsigned pk2(float lo, float hi) { f32x2 v = {lo, hi}; bf16x2_t b = __builtin_convertvector(v, bf16x2_t); return __builtin_bit_cast(unsigned, b); }
; __device__ __forceinline__ void diff_unit(LAS unsigned char* lds, const bf16_t* zA, bf16_t* ya, int bl, int h, int qt, float slope, float lam, float oml, const float* subln, int tid) {
;     ...
;     const float rn = oml / sqrtf(ss * (1.f / 128.f) + 1e-6f);
;     bf16_t* yp = ya + (rb + qpos) * 1536 + h * 128 + quad * 4;
; #pragma unroll
;     for (int d = 0; d < 8; ++d) { const f32x4 g = *(const f32x4*)(subln + d * 16 + quad * 4); u32x2 w; w.x = pk2(oa[d][0] * rn * g[0], oa[d][1] * rn * g[1]); w.y = pk2(oa[d][2] * rn * g[2], oa[d][3] * rn * g[3]); *(u32x2*)(yp + d * 16) = w; }
	v_cndmask_b32_e64 v5, v4, v5, s[42:43]
	v_fma_f32 v4, -v6, v4, v3
	v_cmp_lt_f32_e64 s[42:43], 0, v4
	s_nop 1
	v_cndmask_b32_e64 v4, v5, v6, s[42:43]
	v_mul_f32_e32 v5, 0x37800000, v4
	v_cndmask_b32_e32 v4, v4, v5, vcc
	v_cmp_class_f32_e32 vcc, v3, v180
	s_nop 1
	v_cndmask_b32_e32 v3, v4, v3, vcc
	v_div_scale_f32 v4, s[42:43], v3, v3, v151
	v_rcp_f32_e32 v5, v4
	s_nop 0
	v_fma_f32 v6, -v4, v5, 1.0
	v_fmac_f32_e32 v5, v6, v5
	v_div_scale_f32 v6, vcc, v151, v3, v151
	v_mul_f32_e32 v7, v6, v5
	v_fma_f32 v14, -v4, v7, v6
	v_fmac_f32_e32 v7, v14, v5
	v_fma_f32 v4, -v4, v7, v6
	v_div_fmas_f32 v4, v4, v5, v7
	v_div_fixup_f32 v18, v4, v3, v151
	v_lshl_add_u64 v[4:5], v[132:133], 1, s[76:77]
	v_lshl_add_u64 v[4:5], v[4:5], 0, s[30:31]
	v_lshlrev_b32_e32 v6, 1, v139
	v_mov_b32_e32 v7, v2
	v_lshlrev_b32_e32 v3, 2, v139
	v_lshl_add_u64 v[14:15], v[4:5], 0, v[6:7]
	s_waitcnt vmcnt(0)
	v_mov_b32_e32 v4, v192
	v_mov_b32_e32 v5, v193
	v_mov_b32_e32 v6, v194
	v_mov_b32_e32 v7, v195
	v_pk_mul_f32 v[24:25], v[18:19], v[70:71] op_sel_hi:[0,1]
	v_pk_mul_f32 v[22:23], v[18:19], v[22:23] op_sel_hi:[0,1]
	v_pk_mul_f32 v[20:21], v[18:19], v[20:21] op_sel_hi:[0,1]
	v_pk_mul_f32 v[16:17], v[18:19], v[16:17] op_sel_hi:[0,1]
	v_pk_mul_f32 v[12:13], v[18:19], v[12:13] op_sel_hi:[0,1]
	v_pk_mul_f32 v[10:11], v[18:19], v[10:11] op_sel_hi:[0,1]
	v_pk_mul_f32 v[8:9], v[18:19], v[8:9] op_sel_hi:[0,1]
	v_pk_mul_f32 v[0:1], v[18:19], v[0:1] op_sel_hi:[0,1]
	v_pk_mul_f32 v[4:5], v[4:5], v[24:25]
	v_pk_mul_f32 v[24:25], v[18:19], v[68:69] op_sel_hi:[0,1]
	v_pk_mul_f32 v[6:7], v[6:7], v[24:25]
	v_cvt_pk_bf16_f32 v4, v4, v5
	v_cvt_pk_bf16_f32 v5, v6, v7
	global_store_dwordx2 v[14:15], v[4:5], off
	v_mov_b32_e32 v4, v196
	v_mov_b32_e32 v5, v197
	v_mov_b32_e32 v6, v198
	v_mov_b32_e32 v7, v199
	v_pk_mul_f32 v[24:25], v[18:19], v[66:67] op_sel_hi:[0,1]
	v_pk_mul_f32 v[4:5], v[4:5], v[24:25]
	v_pk_mul_f32 v[24:25], v[18:19], v[64:65] op_sel_hi:[0,1]
	v_pk_mul_f32 v[6:7], v[6:7], v[24:25]
	v_cvt_pk_bf16_f32 v4, v4, v5
	v_cvt_pk_bf16_f32 v5, v6, v7
	global_store_dwordx2 v[14:15], v[4:5], off offset:32
	v_mov_b32_e32 v4, v200
	v_mov_b32_e32 v5, v201
	v_mov_b32_e32 v6, v202
	v_mov_b32_e32 v7, v203
	v_pk_mul_f32 v[24:25], v[18:19], v[38:39] op_sel_hi:[0,1]
	v_pk_mul_f32 v[4:5], v[4:5], v[24:25]
	v_pk_mul_f32 v[24:25], v[18:19], v[36:37] op_sel_hi:[0,1]
	v_pk_mul_f32 v[6:7], v[6:7], v[24:25]
	v_cvt_pk_bf16_f32 v4, v4, v5
	v_cvt_pk_bf16_f32 v5, v6, v7
	global_store_dwordx2 v[14:15], v[4:5], off offset:64
	v_mov_b32_e32 v4, v204
	v_mov_b32_e32 v5, v205
	v_mov_b32_e32 v6, v206
	v_mov_b32_e32 v7, v207
	v_pk_mul_f32 v[24:25], v[18:19], v[34:35] op_sel_hi:[0,1]
	v_pk_mul_f32 v[4:5], v[4:5], v[24:25]
	v_pk_mul_f32 v[24:25], v[18:19], v[32:33] op_sel_hi:[0,1]
	v_pk_mul_f32 v[6:7], v[6:7], v[24:25]
	v_cvt_pk_bf16_f32 v4, v4, v5
	v_cvt_pk_bf16_f32 v5, v6, v7
	global_store_dwordx2 v[14:15], v[4:5], off offset:96
	v_mov_b32_e32 v4, v208
	v_mov_b32_e32 v5, v209
	v_mov_b32_e32 v6, v210
	v_mov_b32_e32 v7, v211
	v_pk_mul_f32 v[24:25], v[18:19], v[28:29] op_sel_hi:[0,1]
	v_pk_mul_f32 v[4:5], v[24:25], v[4:5]
	v_pk_mul_f32 v[6:7], v[22:23], v[6:7]
	v_cvt_pk_bf16_f32 v4, v4, v5
	v_cvt_pk_bf16_f32 v5, v6, v7
	global_store_dwordx2 v[14:15], v[4:5], off offset:128
	v_mov_b32_e32 v4, v212
	v_mov_b32_e32 v5, v213
	v_mov_b32_e32 v6, v214
	v_mov_b32_e32 v7, v215
	v_pk_mul_f32 v[4:5], v[20:21], v[4:5]
	v_pk_mul_f32 v[6:7], v[16:17], v[6:7]
	v_cvt_pk_bf16_f32 v4, v4, v5
	v_cvt_pk_bf16_f32 v5, v6, v7
	global_store_dwordx2 v[14:15], v[4:5], off offset:160
	v_mov_b32_e32 v4, v216
	v_mov_b32_e32 v5, v217
	v_mov_b32_e32 v6, v218
	v_mov_b32_e32 v7, v219
	v_pk_mul_f32 v[4:5], v[12:13], v[4:5]
	v_pk_mul_f32 v[6:7], v[10:11], v[6:7]
	v_cvt_pk_bf16_f32 v4, v4, v5
	v_cvt_pk_bf16_f32 v5, v6, v7
	global_store_dwordx2 v[14:15], v[4:5], off offset:192
	v_mov_b32_e32 v4, v220
	v_mov_b32_e32 v5, v221
	v_mov_b32_e32 v6, v222
	v_mov_b32_e32 v7, v223
	v_pk_mul_f32 v[4:5], v[8:9], v[4:5]
	v_pk_mul_f32 v[0:1], v[0:1], v[6:7]
	v_cvt_pk_bf16_f32 v4, v4, v5
	v_cvt_pk_bf16_f32 v5, v0, v1
	global_store_dwordx2 v[14:15], v[4:5], off offset:224
	s_cbranch_execnz .LBB0_160
	s_branch .LBB0_188
